# attention causal mask on diagonal tiles: one key-query difference per lane, then constant compares into rotating SGPR pairs + selects (was subtract + compare + pad + select per score)
# speedup vs baseline: 1.0021x; 1.0021x over previous
; DI void attn_s(const unsigned char* sK, int tt, int qb, int qs, int sub, int l31, int h,
;                const bf16x8 (&qf)[4], f32x16 (&O)[4], float& m, float& l, bf16x8 (&pb)[4]) {
;     ...
;     } else if (tt >= 2 * qb + 1) {
;         const int kbase = (tt - 1) * 64 + 4 * h;
; #pragma unroll
;         for (int k2 = 0; k2 < 2; ++k2)
; #pragma unroll
;             for (int i = 0; i < 16; ++i) {
;                 const int key = kbase + k2 * 32 + (i & 3) + 8 * (i >> 2);
;                 if (key > qs) st[k2][i] = -INFINITY;
;             }
; DI void attn_pv(const unsigned char* sV, int l31, int h, const bf16x8 (&pb)[4], f32x16 (&O)[4]) {
;     {
;         const unsigned char* vb = sV + l31 * A_VROWB + 16 * h;
;         bf16x8 va[4], vc[4];
; #pragma unroll
;         for (int d = 0; d < 4; ++d) va[d] = *(const bf16x8*)(vb + d * 32 * A_VROWB);
;         __builtin_amdgcn_sched_barrier(0);
; #pragma unroll
;         for (int d = 0; d < 4; ++d) vc[d] = *(const bf16x8*)(vb + d * 32 * A_VROWB + 32);
.Lpipe_loop:
	s_barrier
	v_add3_u32 v191, s98, v156, v98
	ds_read_b128 v[172:175], v191 offset:17408
	ds_read_b128 v[176:179], v191 offset:22016
	ds_read_b128 v[180:183], v191 offset:26624
	ds_read_b128 v[192:195], v191 offset:31232
	ds_read_b128 v[200:203], v191 offset:17440
	ds_read_b128 v[204:207], v191 offset:22048
	ds_read_b128 v[208:211], v191 offset:26656
	ds_read_b128 v[212:215], v191 offset:31264
	s_add_i32 s14, s12, 0x41
	s_cmp_le_i32 s14, s0
	s_cbranch_scc1 .Lpipe_nomask_l
	v_sub_u32_e32 v159, v158, v138
	v_cmp_lt_i32_e64 vcc, 59, v159
	v_cmp_lt_i32_e64 s[4:5], 58, v159
	v_cmp_lt_i32_e64 s[8:9], 57, v159
	v_cmp_lt_i32_e64 s[14:15], 56, v159
	v_cndmask_b32_e64 v82, v82, v188, vcc
	v_cndmask_b32_e64 v83, v83, v188, s[4:5]
	v_cndmask_b32_e64 v84, v84, v188, s[8:9]
	v_cndmask_b32_e64 v85, v85, v188, s[14:15]
	v_cmp_lt_i32_e64 vcc, 51, v159
	v_cmp_lt_i32_e64 s[4:5], 50, v159
	v_cmp_lt_i32_e64 s[8:9], 49, v159
	v_cmp_lt_i32_e64 s[14:15], 48, v159
	v_cndmask_b32_e64 v86, v86, v188, vcc
	v_cndmask_b32_e64 v87, v87, v188, s[4:5]
	v_cndmask_b32_e64 v88, v88, v188, s[8:9]
	v_cndmask_b32_e64 v89, v89, v188, s[14:15]
	v_cmp_lt_i32_e64 vcc, 43, v159
	v_cmp_lt_i32_e64 s[4:5], 42, v159
	v_cmp_lt_i32_e64 s[8:9], 41, v159
	v_cmp_lt_i32_e64 s[14:15], 40, v159
	v_cndmask_b32_e64 v90, v90, v188, vcc
	v_cndmask_b32_e64 v91, v91, v188, s[4:5]
	v_cndmask_b32_e64 v92, v92, v188, s[8:9]
	v_cndmask_b32_e64 v93, v93, v188, s[14:15]
	v_cmp_lt_i32_e64 vcc, 35, v159
	v_cmp_lt_i32_e64 s[4:5], 34, v159
	v_cmp_lt_i32_e64 s[8:9], 33, v159
	v_cmp_lt_i32_e64 s[14:15], 32, v159
	v_cndmask_b32_e64 v94, v94, v188, vcc
	v_cndmask_b32_e64 v95, v95, v188, s[4:5]
	v_cndmask_b32_e64 v96, v96, v188, s[8:9]
	v_cndmask_b32_e64 v97, v97, v188, s[14:15]
	v_cmp_lt_i32_e64 vcc, 27, v159
	v_cmp_lt_i32_e64 s[4:5], 26, v159
	v_cmp_lt_i32_e64 s[8:9], 25, v159
	v_cmp_lt_i32_e64 s[14:15], 24, v159
	v_cndmask_b32_e64 v66, v66, v188, vcc
	v_cndmask_b32_e64 v67, v67, v188, s[4:5]
	v_cndmask_b32_e64 v68, v68, v188, s[8:9]
	v_cndmask_b32_e64 v69, v69, v188, s[14:15]
	v_cmp_lt_i32_e64 vcc, 19, v159
	v_cmp_lt_i32_e64 s[4:5], 18, v159
	v_cmp_lt_i32_e64 s[8:9], 17, v159
	v_cmp_lt_i32_e64 s[14:15], 16, v159
	v_cndmask_b32_e64 v70, v70, v188, vcc
	v_cndmask_b32_e64 v71, v71, v188, s[4:5]
	v_cndmask_b32_e64 v72, v72, v188, s[8:9]
	v_cndmask_b32_e64 v73, v73, v188, s[14:15]
	v_cmp_lt_i32_e64 vcc, 11, v159
	v_cmp_lt_i32_e64 s[4:5], 10, v159
	v_cmp_lt_i32_e64 s[8:9], 9, v159
	v_cmp_lt_i32_e64 s[14:15], 8, v159
	v_cndmask_b32_e64 v74, v74, v188, vcc
	v_cndmask_b32_e64 v75, v75, v188, s[4:5]
	v_cndmask_b32_e64 v76, v76, v188, s[8:9]
	v_cndmask_b32_e64 v77, v77, v188, s[14:15]
	v_cmp_lt_i32_e64 vcc, 3, v159
	v_cmp_lt_i32_e64 s[4:5], 2, v159
	v_cmp_lt_i32_e64 s[8:9], 1, v159
	v_cmp_lt_i32_e64 s[14:15], 0, v159
	v_cndmask_b32_e64 v78, v78, v188, vcc
	v_cndmask_b32_e64 v79, v79, v188, s[4:5]
	v_cndmask_b32_e64 v80, v80, v188, s[8:9]
	v_cndmask_b32_e64 v81, v81, v188, s[14:15]
